# counter hand-off instead of grid barrier after down (it0,it2) and out-proj (it0): per-XCD last arriver flushes L2 during the partner-exchange wait, barrier site polls a counter
# speedup vs baseline: 1.0040x; 1.0016x over previous
.LBB0_384:
	s_or_b64 exec, exec, s[28:29]
	s_lshr_b32 s100, s22, 3
	s_mul_i32 s100, s100, 0x9000
	s_and_b64 vcc, exec, s[10:11]
	s_cselect_b32 s100, s100, 0
	s_cselect_b32 s101, 0x1000, 0
	v_add_u32_e32 v225, s101, v222
	s_add_u32 s100, s24, s100
	s_addc_u32 s101, s25, 0
	global_load_dwordx4 v[156:159], v222, s[100:101]
	global_load_dwordx4 v[160:163], v222, s[100:101] offset:64
	global_load_dwordx4 v[164:167], v222, s[100:101] offset:512
	global_load_dwordx4 v[168:171], v222, s[100:101] offset:576
	global_load_dwordx4 v[172:175], v225, s[100:101]
	global_load_dwordx4 v[176:179], v225, s[100:101] offset:64
	global_load_dwordx4 v[180:183], v225, s[100:101] offset:512
	global_load_dwordx4 v[184:187], v225, s[100:101] offset:576
	s_cmp_gt_u32 s23, 63
	s_cbranch_scc1 .LBB0_394
	s_mov_b64 vcc, exec
	s_mov_b64 exec, 1
	s_load_dwordx2 s[36:37], s[76:77], 0xc8
	s_getreg_b32 s6, hwreg(HW_REG_XCC_ID, 0, 4)
	v_mov_b32_e32 v140, 0x253c0
	ds_read_b32 v141, v140
	s_lshl_b32 s6, s6, 8
	s_add_u32 s6, s6, 0xe000
	v_mov_b32_e32 v140, s6
	v_mov_b32_e32 v142, 1
	s_waitcnt lgkmcnt(0)
	global_atomic_add v143, v140, v142, s[36:37] sc0
	v_readfirstlane_b32 s100, v141
	s_add_u32 s101, s80, 1
	s_cmp_ge_u32 s80, 1
	s_addc_u32 s101, s101, 0
	s_cmp_eq_u32 s80, 3
	s_addc_u32 s101, s101, 0
	s_mul_i32 s101, s101, s100
	s_waitcnt vmcnt(0)
	v_readfirstlane_b32 s6, v143
	s_add_u32 s6, s6, 1
	s_cmp_lg_u32 s6, s101
	s_cbranch_scc1 .Lcs2_skip_0
	buffer_wbl2 sc1
	s_waitcnt vmcnt(0)
	v_mov_b32_e32 v140, 0x7800
	v_mov_b32_e32 v142, s100
	global_atomic_add v140, v142, s[36:37]
.Lcs2_skip_0:
	s_mov_b64 exec, vcc
	s_lshl_b32 s8, s22, 4
	s_ashr_i32 s9, s8, 31
	s_lshl_b64 s[8:9], s[8:9], 2
	s_add_u32 s28, s21, s8
	s_addc_u32 s29, s39, s9
	s_mov_b32 s21, 0x400001
	s_branch .LBB0_387

.LBB0_410:
	v_readlane_b32 s58, v254, 19
	v_readlane_b32 s60, v254, 17
	s_andn2_b64 vcc, exec, s[10:11]
	s_mov_b32 s37, 0x400000
	s_mov_b32 s40, 0x800000
	s_mov_b32 s41, 0xc00000
	s_mov_b32 s45, 0x1000000
	s_waitcnt lgkmcnt(0)
	s_mov_b32 s31, 0xefa18f08
	s_mov_b32 s29, 0x41000000
	v_readlane_b32 s59, v254, 20
	v_readlane_b32 s61, v254, 18
	s_cbranch_vccnz .LBB0_464
	s_mov_b64 s[4:5], s[76:77]
	s_getreg_b32 s10, hwreg(HW_REG_XCC_ID, 0, 4)
	s_waitcnt vmcnt(0)
	v_readlane_b32 s6, v254, 1
	v_readlane_b32 s7, v254, 2
	s_waitcnt vmcnt(0)
	s_barrier
	s_and_saveexec_b64 s[0:1], s[6:7]
	s_cbranch_execz .LBB0_463
	s_cmp_eq_u32 s80, 1
	s_cbranch_scc1 .Lcw_full_2
	s_load_dwordx2 s[4:5], s[76:77], 0xc8
	s_mov_b32 s9, 0x400
	s_cmp_eq_u32 s80, 0
	s_cselect_b32 s9, 0x100, s9
	v_mov_b32_e32 v2, 0x7800
	s_mov_b32 s100, 0
	s_waitcnt lgkmcnt(0)
.Lcw_spin_2:
	global_load_dword v6, v2, s[4:5] sc1
	s_add_u32 s100, s100, 1
	s_waitcnt vmcnt(0)
	v_readfirstlane_b32 s101, v6
	s_cmp_ge_u32 s101, s9
	s_cbranch_scc1 .Lcw_done_2
	s_sleep 1
	s_cmp_lt_u32 s100, 0x40000
	s_cbranch_scc1 .Lcw_spin_2
.Lcw_done_2:
	buffer_inv sc1
	s_waitcnt vmcnt(0)
	s_branch .Lcw_end_2
.Lcw_full_2:
	s_load_dwordx2 s[4:5], s[76:77], 0xc8
	s_getreg_b32 s9, hwreg(HW_REG_XCC_ID, 0, 4)
	v_mov_b32_e32 v2, 0x253c0
	ds_read_b64 v[0:1], v2
	v_mov_b32_e32 v2, 0
	v_mov_b32_e32 v6, 1
	s_lshl_b32 s9, s9, 8
	s_add_u32 s9, s9, 0x4000
	s_waitcnt lgkmcnt(0)
	s_add_u32 s6, s4, s9
	s_addc_u32 s7, s5, 0
	v_mov_b32_e32 v7, 0x1000
	global_atomic_add v7, v7, v6, s[6:7] offset:1024 sc0
	v_readfirstlane_b32 s10, v0
	v_readfirstlane_b32 s11, v1
	v_cvt_f32_u32_e32 v0, v0
	s_nop 0
	v_rcp_iflag_f32_e32 v0, v0
	s_waitcnt vmcnt(0)
	v_readfirstlane_b32 s12, v7
	v_cvt_f32_u32_e32 v7, v7
	s_nop 1
	v_mul_f32_e32 v7, v7, v0
	s_nop 0
	v_cvt_u32_f32_e32 v7, v7
	s_nop 1
	v_readfirstlane_b32 s13, v7
	s_mul_i32 s15, s13, s10
	s_sub_i32 s14, s12, s15
	s_cmp_lt_i32 s14, 0
	s_cbranch_scc0 .Lgb_q1_s2
	s_add_i32 s13, s13, -1
	s_add_i32 s14, s14, s10

.Lcw_end_2:
.LBB0_463:
	s_or_b64 exec, exec, s[0:1]
	s_waitcnt lgkmcnt(0)
	s_barrier

.LBB0_957:
	s_or_b64 exec, exec, s[16:17]
	s_lshr_b32 s100, s10, 3
	s_mul_i32 s100, s100, 0x9000
	v_add_u32_e32 v225, 0x1000, v222
	s_add_u32 s100, s100, 0x46000
	s_add_u32 s100, s14, s100
	s_addc_u32 s101, s15, 0
	s_add_u32 s100, s18, s100
	s_addc_u32 s101, s19, s101
	global_load_dwordx4 v[156:159], v222, s[100:101]
	global_load_dwordx4 v[160:163], v222, s[100:101] offset:64
	global_load_dwordx4 v[164:167], v222, s[100:101] offset:512
	global_load_dwordx4 v[168:171], v222, s[100:101] offset:576
	global_load_dwordx4 v[172:175], v225, s[100:101]
	global_load_dwordx4 v[176:179], v225, s[100:101] offset:64
	global_load_dwordx4 v[180:183], v225, s[100:101] offset:512
	global_load_dwordx4 v[184:187], v225, s[100:101] offset:576
	s_cmp_gt_u32 s7, 63
	s_cbranch_scc1 .LBB0_967
	s_mov_b64 vcc, exec
	s_mov_b64 exec, 1
	s_load_dwordx2 s[16:17], s[76:77], 0xc8
	s_getreg_b32 s7, hwreg(HW_REG_XCC_ID, 0, 4)
	v_mov_b32_e32 v140, 0x253c0
	ds_read_b32 v141, v140
	s_lshl_b32 s7, s7, 8
	s_add_u32 s7, s7, 0xe000
	v_mov_b32_e32 v140, s7
	v_mov_b32_e32 v142, 1
	s_waitcnt lgkmcnt(0)
	global_atomic_add v143, v140, v142, s[16:17] sc0
	v_readfirstlane_b32 s100, v141
	v_readlane_b32 s101, v254, 11
	s_mul_i32 s101, s101, 3
	s_add_u32 s101, s101, 2
	s_mul_i32 s101, s101, s100
	s_waitcnt vmcnt(0)
	v_readfirstlane_b32 s7, v143
	s_add_u32 s7, s7, 1
	s_cmp_lg_u32 s7, s101
	s_cbranch_scc1 .Lcs2_skip_1
	buffer_wbl2 sc1
	s_waitcnt vmcnt(0)
	v_mov_b32_e32 v140, 0x7800
	v_mov_b32_e32 v142, s100
	global_atomic_add v140, v142, s[16:17]
.Lcs2_skip_1:
	s_mov_b64 exec, vcc
	s_lshl_b32 s16, s10, 4
	s_ashr_i32 s17, s16, 31
	s_lshl_b64 s[16:17], s[16:17], 2
	s_add_u32 s16, s9, s16
	s_addc_u32 s17, s11, s17
	s_mov_b32 s7, 0x400001
	s_branch .LBB0_960

.LBB0_980:
	s_cmp_lg_u32 s80, 0
	s_cbranch_scc1 .Lcw_full_6
	s_load_dwordx2 s[2:3], s[76:77], 0xc8
	s_mov_b32 s9, 0x200
	v_mov_b32_e32 v2, 0x7800
	s_mov_b32 s100, 0
	s_waitcnt lgkmcnt(0)
.Lcw_spin_6:
	global_load_dword v6, v2, s[2:3] sc1
	s_add_u32 s100, s100, 1
	s_waitcnt vmcnt(0)
	v_readfirstlane_b32 s101, v6
	s_cmp_ge_u32 s101, s9
	s_cbranch_scc1 .Lcw_done_6
	s_sleep 1
	s_cmp_lt_u32 s100, 0x40000
	s_cbranch_scc1 .Lcw_spin_6

.Lcw_end_6:
	s_getpc_b64 s[98:99]
